# P10 prompt q-tile loop: hand-written QK^T + window masks + running max (parity-specialised, LDS reads two key tiles ahead, masks only on partial tiles, invalid tile skipped)
# baseline (speedup 1.0000x reference)
.LBB0_1176:
	s_bitcmp1_b32 s34, 0
	s_cbranch_scc1 .Lqk_odd
	s_and_b32 s37, s34, 0x7ffffffe
	s_lshl_b32 s80, s37, 4
	s_add_i32 s36, s34, 1
	s_add_i32 s66, s66, 16
	v_or_b32_e32 v114, s80, v1
	s_sub_i32 s35, 8, s37
	s_cmp_lg_u32 s61, 0
	s_cselect_b32 s35, 0, s35
	v_mad_u64_u32 v[114:115], s[80:81], v114, s3, v[30:31]
	v_sub_u32_e32 v58, v32, v1
	v_mov_b32_e32 v67, v54
	ds_read_b128 v[144:147], v114 offset:0
	ds_read_b128 v[148:151], v114 offset:64
	ds_read_b128 v[152:155], v114 offset:2304
	ds_read_b128 v[156:159], v114 offset:2368
	s_waitcnt lgkmcnt(2)
	v_mfma_f32_16x16x32_bf16 v[102:105], v[144:147], v[14:17], 0
	v_mfma_f32_16x16x32_bf16 v[102:105], v[148:151], v[10:13], v[102:105]
	ds_read_b128 v[144:147], v114 offset:4608
	ds_read_b128 v[148:151], v114 offset:4672
	s_waitcnt lgkmcnt(2)
	v_mfma_f32_16x16x32_bf16 v[106:109], v[152:155], v[14:17], 0
	v_mfma_f32_16x16x32_bf16 v[106:109], v[156:159], v[10:13], v[106:109]
	ds_read_b128 v[152:155], v114 offset:6912
	ds_read_b128 v[156:159], v114 offset:6976
	s_nop 0
	s_cmp_le_u32 s35, 0
	s_cselect_b64 s[80:81], -1, 0
	v_cmp_lt_i32_e64 s[82:83], 0, v58
	s_and_b64 vcc, s[82:83], s[80:81]
	v_cndmask_b32_e32 v59, v54, v102, vcc
	v_cmp_lt_i32_e64 s[82:83], -1, v58
	s_and_b64 vcc, s[82:83], s[80:81]
	v_cndmask_b32_e32 v62, v54, v103, vcc
	v_cmp_lt_i32_e64 s[82:83], -2, v58
	s_and_b64 vcc, s[82:83], s[80:81]
	v_cndmask_b32_e32 v61, v54, v104, vcc
	v_cmp_lt_i32_e64 s[82:83], -3, v58
	s_and_b64 vcc, s[82:83], s[80:81]
	v_cndmask_b32_e32 v60, v54, v105, vcc
	v_max3_f32 v67, v67, v59, v62
	v_max3_f32 v67, v67, v61, v60
	s_waitcnt lgkmcnt(2)
	v_mfma_f32_16x16x32_bf16 v[110:113], v[144:147], v[14:17], 0
	v_mfma_f32_16x16x32_bf16 v[110:113], v[148:151], v[10:13], v[110:113]
	ds_read_b128 v[144:147], v114 offset:9216
	ds_read_b128 v[148:151], v114 offset:9280
	s_cmp_le_u32 s35, 1
	s_cselect_b64 s[80:81], -1, 0
	v_cndmask_b32_e64 v66, v54, v106, s[80:81]
	v_cndmask_b32_e64 v65, v54, v107, s[80:81]
	v_cndmask_b32_e64 v64, v54, v108, s[80:81]
	v_cndmask_b32_e64 v63, v54, v109, s[80:81]
	v_max3_f32 v67, v67, v66, v65
	v_max3_f32 v67, v67, v64, v63
	s_waitcnt lgkmcnt(2)
	v_mfma_f32_16x16x32_bf16 v[102:105], v[152:155], v[14:17], 0
	v_mfma_f32_16x16x32_bf16 v[102:105], v[156:159], v[10:13], v[102:105]
	ds_read_b128 v[152:155], v114 offset:11520
	ds_read_b128 v[156:159], v114 offset:11584
	s_cmp_le_u32 s35, 2
	s_cselect_b64 s[80:81], -1, 0
	v_cndmask_b32_e64 v71, v54, v110, s[80:81]
	v_cndmask_b32_e64 v70, v54, v111, s[80:81]
	v_cndmask_b32_e64 v69, v54, v112, s[80:81]
	v_cndmask_b32_e64 v68, v54, v113, s[80:81]
	v_max3_f32 v67, v67, v71, v70
	v_max3_f32 v67, v67, v69, v68
	s_waitcnt lgkmcnt(2)
	v_mfma_f32_16x16x32_bf16 v[106:109], v[144:147], v[14:17], 0
	v_mfma_f32_16x16x32_bf16 v[106:109], v[148:151], v[10:13], v[106:109]
	ds_read_b128 v[144:147], v114 offset:13824
	ds_read_b128 v[148:151], v114 offset:13888
	s_cmp_le_u32 s35, 3
	s_cselect_b64 s[80:81], -1, 0
	v_cndmask_b32_e64 v75, v54, v102, s[80:81]
	v_cndmask_b32_e64 v74, v54, v103, s[80:81]
	v_cndmask_b32_e64 v73, v54, v104, s[80:81]
	v_cndmask_b32_e64 v72, v54, v105, s[80:81]
	v_max3_f32 v67, v67, v75, v74
	v_max3_f32 v67, v67, v73, v72
	s_waitcnt lgkmcnt(2)
	v_mfma_f32_16x16x32_bf16 v[110:113], v[152:155], v[14:17], 0
	v_mfma_f32_16x16x32_bf16 v[110:113], v[156:159], v[10:13], v[110:113]
	ds_read_b128 v[152:155], v114 offset:16128
	ds_read_b128 v[156:159], v114 offset:16192
	s_cmp_le_u32 s35, 4
	s_cselect_b64 s[80:81], -1, 0
	v_cndmask_b32_e64 v79, v54, v106, s[80:81]
	v_cndmask_b32_e64 v78, v54, v107, s[80:81]
	v_cndmask_b32_e64 v77, v54, v108, s[80:81]
	v_cndmask_b32_e64 v76, v54, v109, s[80:81]
	v_max3_f32 v67, v67, v79, v78
	v_max3_f32 v67, v67, v77, v76
	s_waitcnt lgkmcnt(2)
	v_mfma_f32_16x16x32_bf16 v[102:105], v[144:147], v[14:17], 0
	v_mfma_f32_16x16x32_bf16 v[102:105], v[148:151], v[10:13], v[102:105]
	ds_read_b128 v[144:147], v114 offset:18432
	ds_read_b128 v[148:151], v114 offset:18496
	s_cmp_le_u32 s35, 5
	s_cselect_b64 s[80:81], -1, 0
	v_cndmask_b32_e64 v83, v54, v110, s[80:81]
	v_cndmask_b32_e64 v82, v54, v111, s[80:81]
	v_cndmask_b32_e64 v81, v54, v112, s[80:81]
	v_cndmask_b32_e64 v80, v54, v113, s[80:81]
	v_max3_f32 v67, v67, v83, v82
	v_max3_f32 v67, v67, v81, v80
	s_waitcnt lgkmcnt(2)
	v_mfma_f32_16x16x32_bf16 v[106:109], v[152:155], v[14:17], 0
	v_mfma_f32_16x16x32_bf16 v[106:109], v[156:159], v[10:13], v[106:109]
	s_cmp_le_u32 s35, 6
	s_cselect_b64 s[80:81], -1, 0
	v_cndmask_b32_e64 v87, v54, v102, s[80:81]
	v_cndmask_b32_e64 v86, v54, v103, s[80:81]
	v_cndmask_b32_e64 v85, v54, v104, s[80:81]
	v_cndmask_b32_e64 v84, v54, v105, s[80:81]
	v_max3_f32 v67, v67, v87, v86
	v_max3_f32 v67, v67, v85, v84
	s_waitcnt lgkmcnt(0)
	v_mfma_f32_16x16x32_bf16 v[110:113], v[144:147], v[14:17], 0
	v_mfma_f32_16x16x32_bf16 v[110:113], v[148:151], v[10:13], v[110:113]
	s_cmp_le_u32 s35, 7
	s_cselect_b64 s[80:81], -1, 0
	v_cndmask_b32_e64 v100, v54, v106, s[80:81]
	v_cndmask_b32_e64 v90, v54, v107, s[80:81]
	v_cndmask_b32_e64 v89, v54, v108, s[80:81]
	v_cndmask_b32_e64 v88, v54, v109, s[80:81]
	v_max3_f32 v67, v67, v100, v90
	v_max3_f32 v67, v67, v89, v88
	s_cmp_le_u32 s35, 8
	s_cselect_b64 s[80:81], -1, 0
	v_cmp_gt_i32_e64 s[82:83], 1, v58
	s_and_b64 vcc, s[82:83], s[80:81]
	v_cndmask_b32_e32 v98, v54, v110, vcc
	v_cmp_gt_i32_e64 s[82:83], 0, v58
	s_and_b64 vcc, s[82:83], s[80:81]
	v_cndmask_b32_e32 v99, v54, v111, vcc
	v_cmp_gt_i32_e64 s[82:83], -1, v58
	s_and_b64 vcc, s[82:83], s[80:81]
	v_cndmask_b32_e32 v101, v54, v112, vcc
	v_cmp_gt_i32_e64 s[82:83], -2, v58
	s_and_b64 vcc, s[82:83], s[80:81]
	v_cndmask_b32_e32 v91, v54, v113, vcc
	v_max3_f32 v67, v67, v98, v99
	v_max3_f32 v67, v67, v101, v91
	v_mov_b32_e32 v17, v54
	v_mov_b32_e32 v11, v54
	v_mov_b32_e32 v12, v54
	v_mov_b32_e32 v92, v54
	v_mov_b32_e32 v10, v67
	s_add_i32 s67, s37, 2
	s_add_i32 s76, s37, 4
	s_add_i32 s77, s37, 6
	s_add_i32 s34, s37, 8
	s_cmp_eq_u32 s36, 8
	s_branch .Lqk_done
.Lqk_odd:
	s_and_b32 s37, s34, 0x7ffffffe
	s_lshl_b32 s80, s37, 4
	s_add_i32 s36, s34, 1
	s_add_i32 s66, s66, 16
	v_or_b32_e32 v114, s80, v1
	s_sub_i32 s35, 8, s37
	s_cmp_lg_u32 s61, 0
	s_cselect_b32 s35, 0, s35
	v_mad_u64_u32 v[114:115], s[80:81], v114, s3, v[30:31]
	v_sub_u32_e32 v58, v32, v1
	v_mov_b32_e32 v67, v54
	ds_read_b128 v[144:147], v114 offset:2304
	ds_read_b128 v[148:151], v114 offset:2368
	ds_read_b128 v[152:155], v114 offset:4608
	ds_read_b128 v[156:159], v114 offset:4672
	s_waitcnt lgkmcnt(2)
	v_mfma_f32_16x16x32_bf16 v[102:105], v[144:147], v[14:17], 0
	v_mfma_f32_16x16x32_bf16 v[102:105], v[148:151], v[10:13], v[102:105]
	ds_read_b128 v[144:147], v114 offset:6912
	ds_read_b128 v[148:151], v114 offset:6976
	s_waitcnt lgkmcnt(2)
	v_mfma_f32_16x16x32_bf16 v[106:109], v[152:155], v[14:17], 0
	v_mfma_f32_16x16x32_bf16 v[106:109], v[156:159], v[10:13], v[106:109]
	ds_read_b128 v[152:155], v114 offset:9216
	ds_read_b128 v[156:159], v114 offset:9280
	s_nop 0
	s_cmp_le_u32 s35, 1
	s_cselect_b64 s[80:81], -1, 0
	v_cmp_lt_i32_e64 s[82:83], 0, v58
	s_and_b64 vcc, s[82:83], s[80:81]
	v_cndmask_b32_e32 v66, v54, v102, vcc
	v_cmp_lt_i32_e64 s[82:83], -1, v58
	s_and_b64 vcc, s[82:83], s[80:81]
	v_cndmask_b32_e32 v65, v54, v103, vcc
	v_cmp_lt_i32_e64 s[82:83], -2, v58
	s_and_b64 vcc, s[82:83], s[80:81]
	v_cndmask_b32_e32 v64, v54, v104, vcc
	v_cmp_lt_i32_e64 s[82:83], -3, v58
	s_and_b64 vcc, s[82:83], s[80:81]
	v_cndmask_b32_e32 v63, v54, v105, vcc
	v_max3_f32 v67, v67, v66, v65
	v_max3_f32 v67, v67, v64, v63
	s_waitcnt lgkmcnt(2)
	v_mfma_f32_16x16x32_bf16 v[110:113], v[144:147], v[14:17], 0
	v_mfma_f32_16x16x32_bf16 v[110:113], v[148:151], v[10:13], v[110:113]
	ds_read_b128 v[144:147], v114 offset:11520
	ds_read_b128 v[148:151], v114 offset:11584
	s_cmp_le_u32 s35, 2
	s_cselect_b64 s[80:81], -1, 0
	v_cndmask_b32_e64 v71, v54, v106, s[80:81]
	v_cndmask_b32_e64 v70, v54, v107, s[80:81]
	v_cndmask_b32_e64 v69, v54, v108, s[80:81]
	v_cndmask_b32_e64 v68, v54, v109, s[80:81]
	v_max3_f32 v67, v67, v71, v70
	v_max3_f32 v67, v67, v69, v68
	s_waitcnt lgkmcnt(2)
	v_mfma_f32_16x16x32_bf16 v[102:105], v[152:155], v[14:17], 0
	v_mfma_f32_16x16x32_bf16 v[102:105], v[156:159], v[10:13], v[102:105]
	ds_read_b128 v[152:155], v114 offset:13824
	ds_read_b128 v[156:159], v114 offset:13888
	s_cmp_le_u32 s35, 3
	s_cselect_b64 s[80:81], -1, 0
	v_cndmask_b32_e64 v75, v54, v110, s[80:81]
	v_cndmask_b32_e64 v74, v54, v111, s[80:81]
	v_cndmask_b32_e64 v73, v54, v112, s[80:81]
	v_cndmask_b32_e64 v72, v54, v113, s[80:81]
	v_max3_f32 v67, v67, v75, v74
	v_max3_f32 v67, v67, v73, v72
	s_waitcnt lgkmcnt(2)
	v_mfma_f32_16x16x32_bf16 v[106:109], v[144:147], v[14:17], 0
	v_mfma_f32_16x16x32_bf16 v[106:109], v[148:151], v[10:13], v[106:109]
	ds_read_b128 v[144:147], v114 offset:16128
	ds_read_b128 v[148:151], v114 offset:16192
	s_cmp_le_u32 s35, 4
	s_cselect_b64 s[80:81], -1, 0
	v_cndmask_b32_e64 v79, v54, v102, s[80:81]
	v_cndmask_b32_e64 v78, v54, v103, s[80:81]
	v_cndmask_b32_e64 v77, v54, v104, s[80:81]
	v_cndmask_b32_e64 v76, v54, v105, s[80:81]
	v_max3_f32 v67, v67, v79, v78
	v_max3_f32 v67, v67, v77, v76
	s_waitcnt lgkmcnt(2)
	v_mfma_f32_16x16x32_bf16 v[110:113], v[152:155], v[14:17], 0
	v_mfma_f32_16x16x32_bf16 v[110:113], v[156:159], v[10:13], v[110:113]
	ds_read_b128 v[152:155], v114 offset:18432
	ds_read_b128 v[156:159], v114 offset:18496
	s_cmp_le_u32 s35, 5
	s_cselect_b64 s[80:81], -1, 0
	v_cndmask_b32_e64 v83, v54, v106, s[80:81]
	v_cndmask_b32_e64 v82, v54, v107, s[80:81]
	v_cndmask_b32_e64 v81, v54, v108, s[80:81]
	v_cndmask_b32_e64 v80, v54, v109, s[80:81]
	v_max3_f32 v67, v67, v83, v82
	v_max3_f32 v67, v67, v81, v80
	s_waitcnt lgkmcnt(2)
	v_mfma_f32_16x16x32_bf16 v[102:105], v[144:147], v[14:17], 0
	v_mfma_f32_16x16x32_bf16 v[102:105], v[148:151], v[10:13], v[102:105]
	ds_read_b128 v[144:147], v114 offset:20736
	ds_read_b128 v[148:151], v114 offset:20800
	s_cmp_le_u32 s35, 6
	s_cselect_b64 s[80:81], -1, 0
	v_cndmask_b32_e64 v87, v54, v110, s[80:81]
	v_cndmask_b32_e64 v86, v54, v111, s[80:81]
	v_cndmask_b32_e64 v85, v54, v112, s[80:81]
	v_cndmask_b32_e64 v84, v54, v113, s[80:81]
	v_max3_f32 v67, v67, v87, v86
	v_max3_f32 v67, v67, v85, v84
	s_waitcnt lgkmcnt(2)
	v_mfma_f32_16x16x32_bf16 v[106:109], v[152:155], v[14:17], 0
	v_mfma_f32_16x16x32_bf16 v[106:109], v[156:159], v[10:13], v[106:109]
	s_cmp_le_u32 s35, 7
	s_cselect_b64 s[80:81], -1, 0
	v_cndmask_b32_e64 v100, v54, v102, s[80:81]
	v_cndmask_b32_e64 v90, v54, v103, s[80:81]
	v_cndmask_b32_e64 v89, v54, v104, s[80:81]
	v_cndmask_b32_e64 v88, v54, v105, s[80:81]
	v_max3_f32 v67, v67, v100, v90
	v_max3_f32 v67, v67, v89, v88
	s_waitcnt lgkmcnt(0)
	v_mfma_f32_16x16x32_bf16 v[110:113], v[144:147], v[14:17], 0
	v_mfma_f32_16x16x32_bf16 v[110:113], v[148:151], v[10:13], v[110:113]
	s_cmp_le_u32 s35, 8
	s_cselect_b64 s[80:81], -1, 0
	v_cndmask_b32_e64 v98, v54, v106, s[80:81]
	v_cndmask_b32_e64 v99, v54, v107, s[80:81]
	v_cndmask_b32_e64 v101, v54, v108, s[80:81]
	v_cndmask_b32_e64 v91, v54, v109, s[80:81]
	v_max3_f32 v67, v67, v98, v99
	v_max3_f32 v67, v67, v101, v91
	s_cmp_le_u32 s35, 9
	s_cselect_b64 s[80:81], -1, 0
	v_cmp_gt_i32_e64 s[82:83], 1, v58
	s_and_b64 vcc, s[82:83], s[80:81]
	v_cndmask_b32_e32 v17, v54, v110, vcc
	v_cmp_gt_i32_e64 s[82:83], 0, v58
	s_and_b64 vcc, s[82:83], s[80:81]
	v_cndmask_b32_e32 v11, v54, v111, vcc
	v_cmp_gt_i32_e64 s[82:83], -1, v58
	s_and_b64 vcc, s[82:83], s[80:81]
	v_cndmask_b32_e32 v12, v54, v112, vcc
	v_cmp_gt_i32_e64 s[82:83], -2, v58
	s_and_b64 vcc, s[82:83], s[80:81]
	v_cndmask_b32_e32 v92, v54, v113, vcc
	v_max3_f32 v67, v67, v17, v11
	v_max3_f32 v67, v67, v12, v92
	v_mov_b32_e32 v59, v54
	v_mov_b32_e32 v62, v54
	v_mov_b32_e32 v61, v54
	v_mov_b32_e32 v60, v54
	v_mov_b32_e32 v10, v67
	s_add_i32 s67, s37, 2
	s_add_i32 s76, s37, 4
	s_add_i32 s77, s37, 6
	s_add_i32 s34, s37, 8
	s_cmp_eq_u32 s36, 8
.Lqk_done:
	ds_bpermute_b32 v13, v55, v10
	s_waitcnt lgkmcnt(0)
	v_max_f32_e32 v13, v13, v13
	v_max_f32_e32 v10, v10, v13
	ds_bpermute_b32 v13, v56, v10
	s_waitcnt vmcnt(0) lgkmcnt(0)
	v_max3_f32 v10, v10, v13, v37
	v_sub_f32_e32 v14, v62, v10
	v_mul_f32_e32 v14, 0x3fb8aa3b, v14
	v_exp_f32_e32 v94, v14
	v_sub_f32_e32 v14, v61, v10
	v_mul_f32_e32 v14, 0x3fb8aa3b, v14
	v_exp_f32_e32 v95, v14
	v_sub_f32_e32 v14, v60, v10
	v_mul_f32_e32 v14, 0x3fb8aa3b, v14
	v_exp_f32_e32 v96, v14
	v_sub_f32_e32 v14, v66, v10
	v_mul_f32_e32 v14, 0x3fb8aa3b, v14
	v_exp_f32_e32 v97, v14
	v_sub_f32_e32 v14, v65, v10
	v_mul_f32_e32 v14, 0x3fb8aa3b, v14
	v_exp_f32_e32 v102, v14
	v_sub_f32_e32 v14, v64, v10
	v_mul_f32_e32 v14, 0x3fb8aa3b, v14
	v_exp_f32_e32 v103, v14
	v_sub_f32_e32 v14, v63, v10
	v_mul_f32_e32 v14, 0x3fb8aa3b, v14
	v_exp_f32_e32 v104, v14
	v_sub_f32_e32 v14, v71, v10
	v_mul_f32_e32 v14, 0x3fb8aa3b, v14
	v_exp_f32_e32 v105, v14
	v_sub_f32_e32 v14, v70, v10
	v_mul_f32_e32 v14, 0x3fb8aa3b, v14
	v_exp_f32_e32 v106, v14
	v_sub_f32_e32 v14, v69, v10
	v_mul_f32_e32 v14, 0x3fb8aa3b, v14
	v_exp_f32_e32 v107, v14
	v_sub_f32_e32 v14, v68, v10
	v_mul_f32_e32 v14, 0x3fb8aa3b, v14
	v_exp_f32_e32 v108, v14
	v_sub_f32_e32 v14, v75, v10
	v_mul_f32_e32 v14, 0x3fb8aa3b, v14
	v_exp_f32_e32 v109, v14
	v_sub_f32_e32 v14, v74, v10
	v_mul_f32_e32 v14, 0x3fb8aa3b, v14
	v_exp_f32_e32 v110, v14
	v_sub_f32_e32 v14, v73, v10
	v_mul_f32_e32 v14, 0x3fb8aa3b, v14
	v_exp_f32_e32 v111, v14
	v_sub_f32_e32 v14, v72, v10
	v_sub_f32_e32 v13, v59, v10
	v_mul_f32_e32 v14, 0x3fb8aa3b, v14
	v_mul_f32_e32 v13, 0x3fb8aa3b, v13
	v_exp_f32_e32 v112, v14
	v_sub_f32_e32 v14, v79, v10
	v_exp_f32_e32 v93, v13
	v_mul_f32_e32 v14, 0x3fb8aa3b, v14
	v_exp_f32_e32 v66, v14
	v_sub_f32_e32 v14, v78, v10
	v_mul_f32_e32 v14, 0x3fb8aa3b, v14
	v_exp_f32_e32 v69, v14
	v_sub_f32_e32 v14, v77, v10
	v_add_f32_e32 v13, 0, v93
	v_mul_f32_e32 v14, 0x3fb8aa3b, v14
	v_add_f32_e32 v13, v94, v13
	v_exp_f32_e32 v71, v14
	v_sub_f32_e32 v14, v76, v10
	v_add_f32_e32 v13, v95, v13
	v_mul_f32_e32 v14, 0x3fb8aa3b, v14
	v_add_f32_e32 v13, v96, v13
	v_exp_f32_e32 v72, v14
	v_sub_f32_e32 v14, v83, v10
	v_add_f32_e32 v13, v97, v13
	v_mul_f32_e32 v14, 0x3fb8aa3b, v14
	v_add_f32_e32 v13, v102, v13
	v_exp_f32_e32 v73, v14
	v_sub_f32_e32 v14, v82, v10
	v_add_f32_e32 v13, v103, v13
	v_mul_f32_e32 v14, 0x3fb8aa3b, v14
	v_add_f32_e32 v13, v104, v13
	v_exp_f32_e32 v113, v14
	v_sub_f32_e32 v14, v81, v10
	v_add_f32_e32 v13, v105, v13
	v_mul_f32_e32 v14, 0x3fb8aa3b, v14
	v_add_f32_e32 v13, v106, v13
	v_exp_f32_e32 v114, v14
	v_sub_f32_e32 v14, v80, v10
	v_add_f32_e32 v13, v107, v13
	v_mul_f32_e32 v14, 0x3fb8aa3b, v14
	v_add_f32_e32 v13, v108, v13
	v_exp_f32_e32 v115, v14
	v_sub_f32_e32 v14, v87, v10
	v_add_f32_e32 v13, v109, v13
	v_mul_f32_e32 v14, 0x3fb8aa3b, v14
	v_add_f32_e32 v13, v110, v13
	v_exp_f32_e32 v61, v14
	v_sub_f32_e32 v14, v86, v10
	v_add_f32_e32 v13, v111, v13
	v_mul_f32_e32 v14, 0x3fb8aa3b, v14
	v_add_f32_e32 v13, v112, v13
	v_exp_f32_e32 v62, v14
	v_sub_f32_e32 v14, v85, v10
	v_add_f32_e32 v13, v66, v13
	v_mul_f32_e32 v14, 0x3fb8aa3b, v14
	v_add_f32_e32 v13, v69, v13
	v_exp_f32_e32 v63, v14
	v_sub_f32_e32 v14, v84, v10
	v_add_f32_e32 v13, v71, v13
	v_mul_f32_e32 v14, 0x3fb8aa3b, v14
	v_add_f32_e32 v13, v72, v13
	v_exp_f32_e32 v64, v14
	v_sub_f32_e32 v14, v100, v10
	v_add_f32_e32 v13, v73, v13
	v_mul_f32_e32 v14, 0x3fb8aa3b, v14
	v_add_f32_e32 v13, v113, v13
	v_exp_f32_e32 v65, v14
	v_sub_f32_e32 v14, v90, v10
	v_add_f32_e32 v13, v114, v13
	v_mul_f32_e32 v14, 0x3fb8aa3b, v14
	v_add_f32_e32 v13, v115, v13
	v_exp_f32_e32 v67, v14
	v_sub_f32_e32 v14, v89, v10
	v_add_f32_e32 v13, v61, v13
	v_mul_f32_e32 v14, 0x3fb8aa3b, v14
	v_add_f32_e32 v13, v62, v13
	v_exp_f32_e32 v68, v14
	v_sub_f32_e32 v14, v88, v10
	v_add_f32_e32 v13, v63, v13
	v_mul_f32_e32 v14, 0x3fb8aa3b, v14
	v_add_f32_e32 v13, v64, v13
	v_exp_f32_e32 v70, v14
	v_add_f32_e32 v13, v65, v13
	v_add_f32_e32 v13, v67, v13
	v_add_f32_e32 v13, v68, v13
	v_add_f32_e32 v14, v70, v13
	v_sub_f32_e32 v13, v98, v10
	v_mul_f32_e32 v13, 0x3fb8aa3b, v13
	v_exp_f32_e32 v13, v13
	v_sub_f32_e32 v17, v17, v10
	v_mul_f32_e32 v17, 0x3fb8aa3b, v17
	v_exp_f32_e32 v17, v17
	v_add_f32_e32 v15, v13, v14
	v_sub_f32_e32 v14, v99, v10
	v_mul_f32_e32 v14, 0x3fb8aa3b, v14
	v_exp_f32_e32 v14, v14
	v_sub_f32_e32 v11, v11, v10
	v_mul_f32_e32 v11, 0x3fb8aa3b, v11
	v_lshl_add_u32 v90, s37, 5, v49
	v_add_f32_e32 v16, v14, v15
	v_sub_f32_e32 v15, v101, v10
	v_mul_f32_e32 v15, 0x3fb8aa3b, v15
	v_exp_f32_e32 v15, v15
	v_add_u32_e32 v78, 0x9000, v90
	ds_read2_b64 v[78:81], v78 offset1:4
	v_sub_f32_e32 v12, v12, v10
	v_add_f32_e32 v58, v15, v16
	v_sub_f32_e32 v16, v91, v10
	v_mul_f32_e32 v16, 0x3fb8aa3b, v16
	v_exp_f32_e32 v16, v16
	v_mul_f32_e32 v12, 0x3fb8aa3b, v12
	v_add_u32_e32 v82, 0xb000, v90
	v_add_u32_e32 v86, 0xd000, v90
	v_add_f32_e32 v58, v16, v58
	v_add_f32_e32 v59, v17, v58
	v_exp_f32_e32 v58, v11
	v_add_u32_e32 v90, 0xf000, v90
	v_lshl_add_u32 v98, s67, 5, v49
	v_cvt_pk_bf16_f32 v74, v93, v94
	v_add_f32_e32 v11, v58, v59
	v_exp_f32_e32 v59, v12
	v_sub_f32_e32 v12, v92, v10
	ds_read2_b64 v[82:85], v82 offset0:32 offset1:36
	ds_read2_b64 v[86:89], v86 offset0:64 offset1:68
	ds_read2_b64 v[90:93], v90 offset0:96 offset1:100
	v_add_u32_e32 v94, 0x9000, v98
	v_cvt_pk_bf16_f32 v75, v95, v96
	v_cvt_pk_bf16_f32 v76, v97, v102
	ds_read2_b64 v[94:97], v94 offset1:4
	v_cvt_pk_bf16_f32 v77, v103, v104
	v_cvt_pk_bf16_f32 v62, v61, v62
	v_lshl_add_u32 v61, s77, 5, v49
	s_waitcnt lgkmcnt(4)
	v_mfma_f32_16x16x32_bf16 v[78:81], v[78:81], v[74:77], 0
	v_cvt_pk_bf16_f32 v63, v63, v64
	v_cvt_pk_bf16_f32 v64, v65, v67
	v_cvt_pk_bf16_f32 v65, v68, v70
	s_waitcnt lgkmcnt(3)
	v_mfma_f32_16x16x32_bf16 v[82:85], v[82:85], v[74:77], 0
	v_add_u32_e32 v70, 0xb000, v61
	v_mul_f32_e32 v12, 0x3fb8aa3b, v12
	v_exp_f32_e32 v60, v12
	s_waitcnt lgkmcnt(2)
	v_mfma_f32_16x16x32_bf16 v[86:89], v[86:89], v[74:77], 0
	v_cvt_pk_bf16_f32 v14, v13, v14
	v_lshl_add_u32 v13, s34, 5, v49
	v_add_f32_e32 v11, v59, v11
	s_waitcnt lgkmcnt(1)
	v_mfma_f32_16x16x32_bf16 v[74:77], v[90:93], v[74:77], 0
	v_cvt_pk_bf16_f32 v90, v105, v106
	v_cvt_pk_bf16_f32 v91, v107, v108
	v_cvt_pk_bf16_f32 v92, v109, v110
	v_cvt_pk_bf16_f32 v93, v111, v112
	v_cvt_pk_bf16_f32 v15, v15, v16
	v_cvt_pk_bf16_f32 v16, v17, v58
	s_waitcnt lgkmcnt(0)
	v_mfma_f32_16x16x32_bf16 v[78:81], v[94:97], v[90:93], v[78:81]
	v_add_u32_e32 v94, 0xb000, v98
	ds_read2_b64 v[94:97], v94 offset0:32 offset1:36
	v_add_u32_e32 v58, 0x9000, v13
	s_waitcnt lgkmcnt(0)
	v_mfma_f32_16x16x32_bf16 v[82:85], v[94:97], v[90:93], v[82:85]
	v_add_u32_e32 v94, 0xd000, v98
	ds_read2_b64 v[94:97], v94 offset0:64 offset1:68
	v_add_f32_e32 v11, v60, v11
	s_waitcnt lgkmcnt(0)
	v_mfma_f32_16x16x32_bf16 v[86:89], v[94:97], v[90:93], v[86:89]
	v_add_u32_e32 v94, 0xf000, v98
	ds_read2_b64 v[94:97], v94 offset0:96 offset1:100
	v_cvt_pk_bf16_f32 v17, v59, v60
	s_waitcnt lgkmcnt(0)
	v_mfma_f32_16x16x32_bf16 v[74:77], v[94:97], v[90:93], v[74:77]
	v_cvt_pk_bf16_f32 v90, v66, v69
	v_lshl_add_u32 v66, s76, 5, v49
	v_add_u32_e32 v69, 0x9000, v66
	ds_read2_b64 v[94:97], v69 offset1:4
	v_cvt_pk_bf16_f32 v91, v71, v72
	v_cvt_pk_bf16_f32 v92, v73, v113
	v_cvt_pk_bf16_f32 v93, v114, v115
	v_add_u32_e32 v69, 0xb000, v66
	ds_bpermute_b32 v12, v55, v11
	s_waitcnt lgkmcnt(1)
	v_mfma_f32_16x16x32_bf16 v[78:81], v[94:97], v[90:93], v[78:81]
	ds_read2_b64 v[94:97], v69 offset0:32 offset1:36
	v_add_u32_e32 v69, 0xd000, v66
	v_add_u32_e32 v66, 0xf000, v66
	s_waitcnt lgkmcnt(0)
	v_mfma_f32_16x16x32_bf16 v[82:85], v[94:97], v[90:93], v[82:85]
	ds_read2_b64 v[94:97], v69 offset0:64 offset1:68
	v_add_f32_e32 v11, v11, v12
	ds_bpermute_b32 v12, v56, v11
	s_waitcnt lgkmcnt(1)
	v_mfma_f32_16x16x32_bf16 v[86:89], v[94:97], v[90:93], v[86:89]
	ds_read2_b64 v[94:97], v66 offset0:96 offset1:100
	v_add_u32_e32 v66, 0x9000, v61
	ds_read2_b64 v[66:69], v66 offset1:4
	s_waitcnt lgkmcnt(1)
	v_mfma_f32_16x16x32_bf16 v[72:75], v[94:97], v[90:93], v[74:77]
	v_sub_f32_e32 v10, v37, v10
	v_mul_f32_e32 v10, 0x3fb8aa3b, v10
	v_exp_f32_e32 v10, v10
	s_waitcnt lgkmcnt(0)
	v_mfma_f32_16x16x32_bf16 v[66:69], v[66:69], v[62:65], v[78:81]
	v_add_f32_e32 v11, v11, v12
	v_add_f32_e32 v10, v10, v11
	s_nop 0
	ds_read2_b64 v[76:79], v70 offset0:32 offset1:36
	v_add_u32_e32 v70, 0xd000, v61
	s_waitcnt lgkmcnt(0)
	v_mfma_f32_16x16x32_bf16 v[76:79], v[76:79], v[62:65], v[82:85]
	s_nop 2
	ds_read2_b64 v[80:83], v70 offset0:64 offset1:68
	v_add_u32_e32 v61, 0xf000, v61
	v_add_u32_e32 v70, 0xd000, v13
	s_waitcnt lgkmcnt(0)
	v_mfma_f32_16x16x32_bf16 v[80:83], v[80:83], v[62:65], v[86:89]
	s_nop 2
	ds_read2_b64 v[84:87], v61 offset0:96 offset1:100
	ds_read2_b64 v[58:61], v58 offset1:4
	v_div_scale_f32 v11, s[34:35], v10, v10, 1.0
	s_waitcnt lgkmcnt(0)
	v_mfma_f32_16x16x32_bf16 v[58:61], v[58:61], v[14:17], v[66:69]
	s_nop 2
	v_add_u32_e32 v66, 0xb000, v13
	ds_read2_b64 v[66:69], v66 offset0:32 offset1:36
	v_add_u32_e32 v13, 0xf000, v13
	v_mfma_f32_16x16x32_bf16 v[62:65], v[84:87], v[62:65], v[72:75]
	v_rcp_f32_e32 v12, v11
	s_mov_b32 s34, s36
	s_waitcnt lgkmcnt(0)
	v_mfma_f32_16x16x32_bf16 v[66:69], v[66:69], v[14:17], v[76:79]
	ds_read2_b64 v[70:73], v70 offset0:64 offset1:68
	s_nop 1
	ds_read2_b64 v[74:77], v13 offset0:96 offset1:100
	v_fma_f32 v13, -v11, v12, 1.0
	v_fmac_f32_e32 v12, v13, v12
	v_div_scale_f32 v13, vcc, 1.0, v10, 1.0
	s_waitcnt lgkmcnt(1)
	v_mfma_f32_16x16x32_bf16 v[70:73], v[70:73], v[14:17], v[80:83]
	s_waitcnt lgkmcnt(0)
	v_mfma_f32_16x16x32_bf16 v[14:17], v[74:77], v[14:17], v[62:65]
	s_nop 2
	v_mul_f32_e32 v62, v13, v12
	v_fma_f32 v63, -v11, v62, v13
	v_fmac_f32_e32 v62, v63, v12
	v_fma_f32 v11, -v11, v62, v13
	v_div_fmas_f32 v11, v11, v12, v62
	v_div_fixup_f32 v10, v11, v10, 1.0
	v_pk_mul_f32 v[12:13], v[60:61], v[10:11] op_sel_hi:[1,0]
	v_pk_mul_f32 v[58:59], v[58:59], v[10:11] op_sel_hi:[1,0]
	v_pk_mul_f32 v[16:17], v[10:11], v[16:17] op_sel_hi:[0,1]
	v_cvt_pk_bf16_f32 v58, v58, v59
	v_cvt_pk_bf16_f32 v59, v12, v13
	v_lshl_add_u64 v[12:13], v[38:39], 0, v[40:41]
	global_store_dwordx2 v[12:13], v[58:59], off
	v_pk_mul_f32 v[40:41], v[10:11], v[68:69] op_sel_hi:[0,1]
	v_pk_mul_f32 v[58:59], v[10:11], v[66:67] op_sel_hi:[0,1]
	v_cvt_pk_bf16_f32 v58, v58, v59
	v_cvt_pk_bf16_f32 v59, v40, v41
	global_store_dwordx2 v[12:13], v[58:59], off offset:32
	v_pk_mul_f32 v[40:41], v[10:11], v[72:73] op_sel_hi:[0,1]
	v_pk_mul_f32 v[58:59], v[10:11], v[70:71] op_sel_hi:[0,1]
	v_pk_mul_f32 v[10:11], v[10:11], v[14:15] op_sel_hi:[0,1]
	v_cvt_pk_bf16_f32 v58, v58, v59
	v_cvt_pk_bf16_f32 v59, v40, v41
	v_cvt_pk_bf16_f32 v10, v10, v11
	v_cvt_pk_bf16_f32 v11, v16, v17
	global_store_dwordx2 v[12:13], v[58:59], off offset:64
	global_store_dwordx2 v[12:13], v[10:11], off offset:96
	v_mov_b64_e32 v[16:17], v[8:9]
	v_mov_b64_e32 v[12:13], v[4:5]
	v_mov_b64_e32 v[14:15], v[6:7]
	v_mov_b64_e32 v[10:11], v[2:3]
	s_cbranch_scc1 .LBB0_1112
